# MLA/DSA unit epilogue: 16 gate loads issued up front with counted waits instead of a load-store-load chain
# baseline (speedup 1.0000x reference)
; #define LAS __attribute__((address_space(3)))
; __device__ __forceinline__ unsigned cvtpk(float lo, float hi) { unsigned r; asm("v_cvt_pk_bf16_f32 %0, %1, %2" : "=v"(r) : "v"(lo), "v"(hi)); return r; }
; __device__ __forceinline__ float sum_x32(float v) { const unsigned u = __float_as_uint(v); auto r = __builtin_amdgcn_permlane32_swap(u, u, false, false); return __uint_as_float(r[0]) + __uint_as_float(r[1]); }
; template <int MODE>
; __device__ __forceinline__ void attn_unit(LAS char* lds, const AttnPtrs& A, int b, int qb) {
;     ...
;         st_cur = (st_cur == 2) ? 0 : st_cur + 1; st_nn = (st_nn == 2) ? 0 : st_nn + 1;
;     }
;     ...
;     l1 = sum_x32(l1); const float i1 = 1.0f / l1;
;     float rstd = 1.f;
;     if constexpr (MODE == 2) {
;         LAS float* xb = (LAS float*)lds + (wid >> 1) * 4096 + lane;
;         if (strm == 1) { const float i2 = A.lam * i1;
; #pragma unroll
;             for (int c = 0; c < 4; ++c)
; #pragma unroll
;                 for (int r = 0; r < 16; ++r) xb[(c * 16 + r) * 64] = o1[c][r] * i2; }
;         __syncthreads();
;         if (strm == 0) { float ss = 0.f;
; #pragma unroll
;             for (int c = 0; c < 4; ++c)
; #pragma unroll
;                 for (int r = 0; r < 16; ++r) { const float v = o1[c][r] * i1 - xb[(c * 16 + r) * 64]; o1[c][r] = v; ss += v * v; }
;             ss = sum_x32(ss); rstd = __builtin_amdgcn_rsqf(ss * (1.0f / 128.0f) + 1e-6f) * A.c_out; }
;         __syncthreads();
;         if (strm == 1) return;
;     }
;     const bf16_t* grow = A.G + qrow * 2048; bf16_t* orow = A.Go + qrow * 2048;
; #pragma unroll
;     for (int c = 0; c < 4; ++c)
; #pragma unroll
;         for (int rr = 0; rr < 4; ++rr) {
;             const int dv = 32 * c + 8 * rr + 4 * hi;
;             const u32x2 g = *(const u32x2*)(grow + dv);
;             float v[4];
; #pragma unroll
;             for (int e = 0; e < 4; ++e) v[e] = o1[c][4 * rr + e];
;             if (MODE == 2) { const f32x4 sg = *(const f32x4*)(A.subg + dv);
; #pragma unroll
;                 for (int e = 0; e < 4; ++e) v[e] *= rstd * sg[e]; }
;             else {
; #pragma unroll
;                 for (int e = 0; e < 4; ++e) v[e] *= i1; }
;             u32x2 w; w.x = cvtpk(v[0] * bf_lo(g.x), v[1] * bf_hi(g.x)); w.y = cvtpk(v[2] * bf_lo(g.y), v[3] * bf_hi(g.y));
;             *(u32x2*)(orow + dv) = w;
.LBB0_1184:
	s_add_i32 s0, s17, 1
	s_cmp_lg_u32 s17, 2
	s_cselect_b32 s17, s0, 0
	s_add_i32 s0, s16, 1
	s_barrier
	s_cmp_lg_u32 s16, 2
	s_cselect_b32 s16, s0, 0
	s_add_i32 s50, s50, 1
	v_lshl_add_u64 v[134:135], v[134:135], 0, 8
	v_lshl_add_u64 v[136:137], v[136:137], 0, s[60:61]
	s_cmp_lg_u32 s33, s50
	v_lshl_add_u64 v[138:139], v[138:139], 0, s[60:61]
	s_cbranch_scc1 .LBB0_1170
	v_mov_b32_e32 v0, v183
	s_nop 1
	v_permlane32_swap_b32_e32 v183, v0
	v_add_f32_e32 v0, v183, v0
	v_div_scale_f32 v66, s[12:13], v0, v0, 1.0
	v_rcp_f32_e32 v67, v66
	s_lshl_b32 s0, s15, 1
	s_add_u32 s0, s27, s0
	s_addc_u32 s1, s28, 0
	v_fma_f32 v68, -v66, v67, 1.0
	v_fmac_f32_e32 v67, v68, v67
	v_div_scale_f32 v68, vcc, 1.0, v0, 1.0
	v_mul_f32_e32 v69, v68, v67
	v_fma_f32 v70, -v66, v69, v68
	v_fmac_f32_e32 v69, v70, v67
	v_fma_f32 v66, -v66, v69, v68
	v_div_fmas_f32 v66, v66, v67, v69
	v_div_fixup_f32 v68, v66, v0, 1.0
	v_lshlrev_b64 v[66:67], 12, v[130:131]
	v_lshl_add_u64 v[66:67], s[0:1], 0, v[66:67]
	v_lshlrev_b32_e32 v0, 1, v140
	v_lshl_add_u64 v[66:67], v[66:67], 0, v[0:1]
	s_mov_b64 s[0:1], 0
	global_load_dwordx2 v[70:71], v[66:67], off
	global_load_dwordx2 v[72:73], v[66:67], off offset:16
	global_load_dwordx2 v[74:75], v[66:67], off offset:32
	global_load_dwordx2 v[76:77], v[66:67], off offset:48
	global_load_dwordx2 v[78:79], v[66:67], off offset:64
	global_load_dwordx2 v[80:81], v[66:67], off offset:80
	global_load_dwordx2 v[82:83], v[66:67], off offset:96
	global_load_dwordx2 v[84:85], v[66:67], off offset:112
	global_load_dwordx2 v[86:87], v[66:67], off offset:128
	global_load_dwordx2 v[88:89], v[66:67], off offset:144
	global_load_dwordx2 v[90:91], v[66:67], off offset:160
	global_load_dwordx2 v[92:93], v[66:67], off offset:176
	global_load_dwordx2 v[94:95], v[66:67], off offset:192
	global_load_dwordx2 v[96:97], v[66:67], off offset:208
	global_load_dwordx2 v[160:161], v[66:67], off offset:224
	global_load_dwordx2 v[162:163], v[66:67], off offset:240
	v_mul_f32_e32 v164, v50, v68
	v_mul_f32_e32 v165, v51, v68
	v_mul_f32_e32 v166, v52, v68
	v_mul_f32_e32 v167, v53, v68
	s_waitcnt vmcnt(15)
	v_lshlrev_b32_e32 v168, 16, v70
	v_and_b32_e32 v169, 0xffff0000, v70
	v_lshlrev_b32_e32 v170, 16, v71
	v_and_b32_e32 v171, 0xffff0000, v71
	v_mul_f32_e32 v164, v164, v168
	v_mul_f32_e32 v165, v165, v169
	v_mul_f32_e32 v166, v166, v170
	v_mul_f32_e32 v167, v167, v171
	v_cvt_pk_bf16_f32 v70, v164, v165
	v_cvt_pk_bf16_f32 v71, v166, v167
	global_store_dwordx2 v[66:67], v[70:71], off
	v_mul_f32_e32 v164, v54, v68
	v_mul_f32_e32 v165, v55, v68
	v_mul_f32_e32 v166, v56, v68
	v_mul_f32_e32 v167, v57, v68
	s_waitcnt vmcnt(15)
	v_lshlrev_b32_e32 v168, 16, v72
	v_and_b32_e32 v169, 0xffff0000, v72
	v_lshlrev_b32_e32 v170, 16, v73
	v_and_b32_e32 v171, 0xffff0000, v73
	v_mul_f32_e32 v164, v164, v168
	v_mul_f32_e32 v165, v165, v169
	v_mul_f32_e32 v166, v166, v170
	v_mul_f32_e32 v167, v167, v171
	v_cvt_pk_bf16_f32 v72, v164, v165
	v_cvt_pk_bf16_f32 v73, v166, v167
	global_store_dwordx2 v[66:67], v[72:73], off offset:16
	v_mul_f32_e32 v164, v58, v68
	v_mul_f32_e32 v165, v59, v68
	v_mul_f32_e32 v166, v60, v68
	v_mul_f32_e32 v167, v61, v68
	s_waitcnt vmcnt(15)
	v_lshlrev_b32_e32 v168, 16, v74
	v_and_b32_e32 v169, 0xffff0000, v74
	v_lshlrev_b32_e32 v170, 16, v75
	v_and_b32_e32 v171, 0xffff0000, v75
	v_mul_f32_e32 v164, v164, v168
	v_mul_f32_e32 v165, v165, v169
	v_mul_f32_e32 v166, v166, v170
	v_mul_f32_e32 v167, v167, v171
	v_cvt_pk_bf16_f32 v74, v164, v165
	v_cvt_pk_bf16_f32 v75, v166, v167
	global_store_dwordx2 v[66:67], v[74:75], off offset:32
	v_mul_f32_e32 v164, v62, v68
	v_mul_f32_e32 v165, v63, v68
	v_mul_f32_e32 v166, v64, v68
	v_mul_f32_e32 v167, v65, v68
	s_waitcnt vmcnt(15)
	v_lshlrev_b32_e32 v168, 16, v76
	v_and_b32_e32 v169, 0xffff0000, v76
	v_lshlrev_b32_e32 v170, 16, v77
	v_and_b32_e32 v171, 0xffff0000, v77
	v_mul_f32_e32 v164, v164, v168
	v_mul_f32_e32 v165, v165, v169
	v_mul_f32_e32 v166, v166, v170
	v_mul_f32_e32 v167, v167, v171
	v_cvt_pk_bf16_f32 v76, v164, v165
	v_cvt_pk_bf16_f32 v77, v166, v167
	global_store_dwordx2 v[66:67], v[76:77], off offset:48
	v_mul_f32_e32 v164, v34, v68
	v_mul_f32_e32 v165, v35, v68
	v_mul_f32_e32 v166, v36, v68
	v_mul_f32_e32 v167, v37, v68
	s_waitcnt vmcnt(15)
	v_lshlrev_b32_e32 v168, 16, v78
	v_and_b32_e32 v169, 0xffff0000, v78
	v_lshlrev_b32_e32 v170, 16, v79
	v_and_b32_e32 v171, 0xffff0000, v79
	v_mul_f32_e32 v164, v164, v168
	v_mul_f32_e32 v165, v165, v169
	v_mul_f32_e32 v166, v166, v170
	v_mul_f32_e32 v167, v167, v171
	v_cvt_pk_bf16_f32 v78, v164, v165
	v_cvt_pk_bf16_f32 v79, v166, v167
	global_store_dwordx2 v[66:67], v[78:79], off offset:64
	v_mul_f32_e32 v164, v38, v68
	v_mul_f32_e32 v165, v39, v68
	v_mul_f32_e32 v166, v40, v68
	v_mul_f32_e32 v167, v41, v68
	s_waitcnt vmcnt(15)
	v_lshlrev_b32_e32 v168, 16, v80
	v_and_b32_e32 v169, 0xffff0000, v80
	v_lshlrev_b32_e32 v170, 16, v81
	v_and_b32_e32 v171, 0xffff0000, v81
	v_mul_f32_e32 v164, v164, v168
	v_mul_f32_e32 v165, v165, v169
	v_mul_f32_e32 v166, v166, v170
	v_mul_f32_e32 v167, v167, v171
	v_cvt_pk_bf16_f32 v80, v164, v165
	v_cvt_pk_bf16_f32 v81, v166, v167
	global_store_dwordx2 v[66:67], v[80:81], off offset:80
	v_mul_f32_e32 v164, v42, v68
	v_mul_f32_e32 v165, v43, v68
	v_mul_f32_e32 v166, v44, v68
	v_mul_f32_e32 v167, v45, v68
	s_waitcnt vmcnt(15)
; __device__ __forceinline__ unsigned cvtpk(float lo, float hi) { unsigned r; asm("v_cvt_pk_bf16_f32 %0, %1, %2" : "=v"(r) : "v"(lo), "v"(hi)); return r; }
; __device__ __forceinline__ float bf_lo(unsigned w) { return __uint_as_float(w << 16); }
; __device__ __forceinline__ float bf_hi(unsigned w) { return __uint_as_float(w & 0xffff0000u); }
; template <int MODE>
; __device__ __forceinline__ void attn_unit(LAS char* lds, const AttnPtrs& A, int b, int qb) {
;     ...
;     const bf16_t* grow = A.G + qrow * 2048; bf16_t* orow = A.Go + qrow * 2048;
; #pragma unroll
;     for (int c = 0; c < 4; ++c)
; #pragma unroll
;         for (int rr = 0; rr < 4; ++rr) {
;             const int dv = 32 * c + 8 * rr + 4 * hi;
;             const u32x2 g = *(const u32x2*)(grow + dv);
;             float v[4];
; #pragma unroll
;             for (int e = 0; e < 4; ++e) v[e] = o1[c][4 * rr + e];
;             if (MODE == 2) { const f32x4 sg = *(const f32x4*)(A.subg + dv);
; #pragma unroll
;                 for (int e = 0; e < 4; ++e) v[e] *= rstd * sg[e]; }
;             else {
; #pragma unroll
;                 for (int e = 0; e < 4; ++e) v[e] *= i1; }
;             u32x2 w; w.x = cvtpk(v[0] * bf_lo(g.x), v[1] * bf_hi(g.x)); w.y = cvtpk(v[2] * bf_lo(g.y), v[3] * bf_hi(g.y));
;             *(u32x2*)(orow + dv) = w;
	v_lshlrev_b32_e32 v168, 16, v82
	v_and_b32_e32 v169, 0xffff0000, v82
	v_lshlrev_b32_e32 v170, 16, v83
	v_and_b32_e32 v171, 0xffff0000, v83
	v_mul_f32_e32 v164, v164, v168
	v_mul_f32_e32 v165, v165, v169
	v_mul_f32_e32 v166, v166, v170
	v_mul_f32_e32 v167, v167, v171
	v_cvt_pk_bf16_f32 v82, v164, v165
	v_cvt_pk_bf16_f32 v83, v166, v167
	global_store_dwordx2 v[66:67], v[82:83], off offset:96
	v_mul_f32_e32 v164, v46, v68
	v_mul_f32_e32 v165, v47, v68
	v_mul_f32_e32 v166, v48, v68
	v_mul_f32_e32 v167, v49, v68
	s_waitcnt vmcnt(15)
	v_lshlrev_b32_e32 v168, 16, v84
	v_and_b32_e32 v169, 0xffff0000, v84
	v_lshlrev_b32_e32 v170, 16, v85
	v_and_b32_e32 v171, 0xffff0000, v85
	v_mul_f32_e32 v164, v164, v168
	v_mul_f32_e32 v165, v165, v169
	v_mul_f32_e32 v166, v166, v170
	v_mul_f32_e32 v167, v167, v171
	v_cvt_pk_bf16_f32 v84, v164, v165
	v_cvt_pk_bf16_f32 v85, v166, v167
	global_store_dwordx2 v[66:67], v[84:85], off offset:112
	v_mul_f32_e32 v164, v18, v68
	v_mul_f32_e32 v165, v19, v68
	v_mul_f32_e32 v166, v20, v68
	v_mul_f32_e32 v167, v21, v68
	s_waitcnt vmcnt(15)
	v_lshlrev_b32_e32 v168, 16, v86
	v_and_b32_e32 v169, 0xffff0000, v86
	v_lshlrev_b32_e32 v170, 16, v87
	v_and_b32_e32 v171, 0xffff0000, v87
	v_mul_f32_e32 v164, v164, v168
	v_mul_f32_e32 v165, v165, v169
	v_mul_f32_e32 v166, v166, v170
	v_mul_f32_e32 v167, v167, v171
	v_cvt_pk_bf16_f32 v86, v164, v165
	v_cvt_pk_bf16_f32 v87, v166, v167
	global_store_dwordx2 v[66:67], v[86:87], off offset:128
	v_mul_f32_e32 v164, v22, v68
	v_mul_f32_e32 v165, v23, v68
	v_mul_f32_e32 v166, v24, v68
	v_mul_f32_e32 v167, v25, v68
	s_waitcnt vmcnt(15)
	v_lshlrev_b32_e32 v168, 16, v88
	v_and_b32_e32 v169, 0xffff0000, v88
	v_lshlrev_b32_e32 v170, 16, v89
	v_and_b32_e32 v171, 0xffff0000, v89
	v_mul_f32_e32 v164, v164, v168
	v_mul_f32_e32 v165, v165, v169
	v_mul_f32_e32 v166, v166, v170
	v_mul_f32_e32 v167, v167, v171
	v_cvt_pk_bf16_f32 v88, v164, v165
	v_cvt_pk_bf16_f32 v89, v166, v167
	global_store_dwordx2 v[66:67], v[88:89], off offset:144
	v_mul_f32_e32 v164, v26, v68
	v_mul_f32_e32 v165, v27, v68
	v_mul_f32_e32 v166, v28, v68
	v_mul_f32_e32 v167, v29, v68
	s_waitcnt vmcnt(15)
	v_lshlrev_b32_e32 v168, 16, v90
	v_and_b32_e32 v169, 0xffff0000, v90
	v_lshlrev_b32_e32 v170, 16, v91
	v_and_b32_e32 v171, 0xffff0000, v91
	v_mul_f32_e32 v164, v164, v168
	v_mul_f32_e32 v165, v165, v169
	v_mul_f32_e32 v166, v166, v170
	v_mul_f32_e32 v167, v167, v171
	v_cvt_pk_bf16_f32 v90, v164, v165
	v_cvt_pk_bf16_f32 v91, v166, v167
	global_store_dwordx2 v[66:67], v[90:91], off offset:160
	v_mul_f32_e32 v164, v30, v68
	v_mul_f32_e32 v165, v31, v68
	v_mul_f32_e32 v166, v32, v68
	v_mul_f32_e32 v167, v33, v68
	s_waitcnt vmcnt(15)
	v_lshlrev_b32_e32 v168, 16, v92
	v_and_b32_e32 v169, 0xffff0000, v92
	v_lshlrev_b32_e32 v170, 16, v93
	v_and_b32_e32 v171, 0xffff0000, v93
	v_mul_f32_e32 v164, v164, v168
	v_mul_f32_e32 v165, v165, v169
	v_mul_f32_e32 v166, v166, v170
	v_mul_f32_e32 v167, v167, v171
	v_cvt_pk_bf16_f32 v92, v164, v165
	v_cvt_pk_bf16_f32 v93, v166, v167
	global_store_dwordx2 v[66:67], v[92:93], off offset:176
	v_mul_f32_e32 v164, v2, v68
	v_mul_f32_e32 v165, v3, v68
	v_mul_f32_e32 v166, v4, v68
	v_mul_f32_e32 v167, v5, v68
	s_waitcnt vmcnt(15)
	v_lshlrev_b32_e32 v168, 16, v94
	v_and_b32_e32 v169, 0xffff0000, v94
	v_lshlrev_b32_e32 v170, 16, v95
	v_and_b32_e32 v171, 0xffff0000, v95
	v_mul_f32_e32 v164, v164, v168
	v_mul_f32_e32 v165, v165, v169
	v_mul_f32_e32 v166, v166, v170
	v_mul_f32_e32 v167, v167, v171
	v_cvt_pk_bf16_f32 v94, v164, v165
	v_cvt_pk_bf16_f32 v95, v166, v167
	global_store_dwordx2 v[66:67], v[94:95], off offset:192
	v_mul_f32_e32 v164, v6, v68
	v_mul_f32_e32 v165, v7, v68
	v_mul_f32_e32 v166, v8, v68
	v_mul_f32_e32 v167, v9, v68
	s_waitcnt vmcnt(15)
	v_lshlrev_b32_e32 v168, 16, v96
	v_and_b32_e32 v169, 0xffff0000, v96
	v_lshlrev_b32_e32 v170, 16, v97
	v_and_b32_e32 v171, 0xffff0000, v97
	v_mul_f32_e32 v164, v164, v168
	v_mul_f32_e32 v165, v165, v169
	v_mul_f32_e32 v166, v166, v170
	v_mul_f32_e32 v167, v167, v171
	v_cvt_pk_bf16_f32 v96, v164, v165
	v_cvt_pk_bf16_f32 v97, v166, v167
	global_store_dwordx2 v[66:67], v[96:97], off offset:208
	v_mul_f32_e32 v164, v10, v68
	v_mul_f32_e32 v165, v11, v68
	v_mul_f32_e32 v166, v12, v68
	v_mul_f32_e32 v167, v13, v68
	s_waitcnt vmcnt(15)
	v_lshlrev_b32_e32 v168, 16, v160
	v_and_b32_e32 v169, 0xffff0000, v160
	v_lshlrev_b32_e32 v170, 16, v161
	v_and_b32_e32 v171, 0xffff0000, v161
	v_mul_f32_e32 v164, v164, v168
	v_mul_f32_e32 v165, v165, v169
	v_mul_f32_e32 v166, v166, v170
	v_mul_f32_e32 v167, v167, v171
	v_cvt_pk_bf16_f32 v160, v164, v165
	v_cvt_pk_bf16_f32 v161, v166, v167
	global_store_dwordx2 v[66:67], v[160:161], off offset:224
	v_mul_f32_e32 v164, v14, v68
	v_mul_f32_e32 v165, v15, v68
	v_mul_f32_e32 v166, v16, v68
	v_mul_f32_e32 v167, v17, v68
	s_waitcnt vmcnt(15)
	v_lshlrev_b32_e32 v168, 16, v162
	v_and_b32_e32 v169, 0xffff0000, v162
	v_lshlrev_b32_e32 v170, 16, v163
	v_and_b32_e32 v171, 0xffff0000, v163
	v_mul_f32_e32 v164, v164, v168
	v_mul_f32_e32 v165, v165, v169
	v_mul_f32_e32 v166, v166, v170
	v_mul_f32_e32 v167, v167, v171
	v_cvt_pk_bf16_f32 v162, v164, v165
	v_cvt_pk_bf16_f32 v163, v166, v167
	global_store_dwordx2 v[66:67], v[162:163], off offset:240

; #define LAS __attribute__((address_space(3)))
; __device__ __forceinline__ unsigned cvtpk(float lo, float hi) { unsigned r; asm("v_cvt_pk_bf16_f32 %0, %1, %2" : "=v"(r) : "v"(lo), "v"(hi)); return r; }
; __device__ __forceinline__ float sum_x32(float v) { const unsigned u = __float_as_uint(v); auto r = __builtin_amdgcn_permlane32_swap(u, u, false, false); return __uint_as_float(r[0]) + __uint_as_float(r[1]); }
; __device__ __forceinline__ float bf_lo(unsigned w) { return __uint_as_float(w << 16); }
; template <int MODE>
; __device__ __forceinline__ void attn_unit(LAS char* lds, const AttnPtrs& A, int b, int qb) {
;     ...
;     l1 = sum_x32(l1); const float i1 = 1.0f / l1;
;     float rstd = 1.f;
;     if constexpr (MODE == 2) {
;         LAS float* xb = (LAS float*)lds + (wid >> 1) * 4096 + lane;
;         if (strm == 1) { const float i2 = A.lam * i1;
; #pragma unroll
;             for (int c = 0; c < 4; ++c)
; #pragma unroll
;                 for (int r = 0; r < 16; ++r) xb[(c * 16 + r) * 64] = o1[c][r] * i2; }
;         __syncthreads();
;         if (strm == 0) { float ss = 0.f;
; #pragma unroll
;             for (int c = 0; c < 4; ++c)
; #pragma unroll
;                 for (int r = 0; r < 16; ++r) { const float v = o1[c][r] * i1 - xb[(c * 16 + r) * 64]; o1[c][r] = v; ss += v * v; }
;             ss = sum_x32(ss); rstd = __builtin_amdgcn_rsqf(ss * (1.0f / 128.0f) + 1e-6f) * A.c_out; }
;         __syncthreads();
;         if (strm == 1) return;
;     }
;     const bf16_t* grow = A.G + qrow * 2048; bf16_t* orow = A.Go + qrow * 2048;
; #pragma unroll
;     for (int c = 0; c < 4; ++c)
; #pragma unroll
;         for (int rr = 0; rr < 4; ++rr) {
;             const int dv = 32 * c + 8 * rr + 4 * hi;
;             const u32x2 g = *(const u32x2*)(grow + dv);
;             float v[4];
; #pragma unroll
;             for (int e = 0; e < 4; ++e) v[e] = o1[c][4 * rr + e];
;             if (MODE == 2) { const f32x4 sg = *(const f32x4*)(A.subg + dv);
; #pragma unroll
;                 for (int e = 0; e < 4; ++e) v[e] *= rstd * sg[e]; }
;             else {
; #pragma unroll
;                 for (int e = 0; e < 4; ++e) v[e] *= i1; }
;             u32x2 w; w.x = cvtpk(v[0] * bf_lo(g.x), v[1] * bf_hi(g.x)); w.y = cvtpk(v[2] * bf_lo(g.y), v[3] * bf_hi(g.y));
;             *(u32x2*)(orow + dv) = w;
.LBB0_1200:
	v_mov_b32_e32 v0, v234
	s_nop 1
	v_permlane32_swap_b32_e32 v234, v0
	v_add_f32_e32 v0, v234, v0
	v_div_scale_f32 v2, s[12:13], v0, v0, 1.0
	v_rcp_f32_e32 v3, v2
	s_add_u32 s0, s47, s0
	s_addc_u32 s1, s48, s1
	v_fma_f32 v4, -v2, v3, 1.0
	v_fmac_f32_e32 v3, v4, v3
	v_div_scale_f32 v4, vcc, 1.0, v0, 1.0
	v_mul_f32_e32 v5, v4, v3
	v_fma_f32 v6, -v2, v5, v4
	v_fmac_f32_e32 v5, v6, v3
	v_fma_f32 v2, -v2, v5, v4
	v_div_fmas_f32 v2, v2, v3, v5
	v_div_fixup_f32 v6, v2, v0, 1.0
	v_lshlrev_b64 v[2:3], 12, v[178:179]
	v_lshl_add_u64 v[2:3], s[0:1], 0, v[2:3]
	v_lshlrev_b32_e32 v0, 1, v176
	v_lshl_add_u64 v[2:3], v[2:3], 0, v[0:1]
	global_load_dwordx2 v[80:81], v[2:3], off
	global_load_dwordx2 v[82:83], v[2:3], off offset:16
	global_load_dwordx2 v[84:85], v[2:3], off offset:32
	global_load_dwordx2 v[86:87], v[2:3], off offset:48
	global_load_dwordx2 v[88:89], v[2:3], off offset:64
	global_load_dwordx2 v[90:91], v[2:3], off offset:80
	global_load_dwordx2 v[92:93], v[2:3], off offset:96
	global_load_dwordx2 v[94:95], v[2:3], off offset:112
	global_load_dwordx2 v[96:97], v[2:3], off offset:128
	global_load_dwordx2 v[98:99], v[2:3], off offset:144
	global_load_dwordx2 v[100:101], v[2:3], off offset:160
	global_load_dwordx2 v[102:103], v[2:3], off offset:176
	global_load_dwordx2 v[104:105], v[2:3], off offset:192
	global_load_dwordx2 v[106:107], v[2:3], off offset:208
	global_load_dwordx2 v[108:109], v[2:3], off offset:224
	global_load_dwordx2 v[110:111], v[2:3], off offset:240
	v_mul_f32_e32 v112, v64, v6
	v_mul_f32_e32 v113, v65, v6
	v_mul_f32_e32 v114, v66, v6
	v_mul_f32_e32 v115, v67, v6
	s_waitcnt vmcnt(15)
	v_lshlrev_b32_e32 v116, 16, v80
	v_and_b32_e32 v117, 0xffff0000, v80
	v_lshlrev_b32_e32 v118, 16, v81
	v_and_b32_e32 v119, 0xffff0000, v81
	v_mul_f32_e32 v112, v112, v116
	v_mul_f32_e32 v113, v113, v117
	v_mul_f32_e32 v114, v114, v118
	v_mul_f32_e32 v115, v115, v119
	v_cvt_pk_bf16_f32 v80, v112, v113
	v_cvt_pk_bf16_f32 v81, v114, v115
	global_store_dwordx2 v[2:3], v[80:81], off
	v_mul_f32_e32 v112, v68, v6
	v_mul_f32_e32 v113, v69, v6
	v_mul_f32_e32 v114, v70, v6
	v_mul_f32_e32 v115, v71, v6
	s_waitcnt vmcnt(15)
	v_lshlrev_b32_e32 v116, 16, v82
	v_and_b32_e32 v117, 0xffff0000, v82
	v_lshlrev_b32_e32 v118, 16, v83
	v_and_b32_e32 v119, 0xffff0000, v83
	v_mul_f32_e32 v112, v112, v116
	v_mul_f32_e32 v113, v113, v117
	v_mul_f32_e32 v114, v114, v118
	v_mul_f32_e32 v115, v115, v119
	v_cvt_pk_bf16_f32 v82, v112, v113
	v_cvt_pk_bf16_f32 v83, v114, v115
	global_store_dwordx2 v[2:3], v[82:83], off offset:16
	v_mul_f32_e32 v112, v72, v6
	v_mul_f32_e32 v113, v73, v6
	v_mul_f32_e32 v114, v74, v6
	v_mul_f32_e32 v115, v75, v6
	s_waitcnt vmcnt(15)
	v_lshlrev_b32_e32 v116, 16, v84
	v_and_b32_e32 v117, 0xffff0000, v84
	v_lshlrev_b32_e32 v118, 16, v85
	v_and_b32_e32 v119, 0xffff0000, v85
	v_mul_f32_e32 v112, v112, v116
	v_mul_f32_e32 v113, v113, v117
	v_mul_f32_e32 v114, v114, v118
	v_mul_f32_e32 v115, v115, v119
	v_cvt_pk_bf16_f32 v84, v112, v113
	v_cvt_pk_bf16_f32 v85, v114, v115
	global_store_dwordx2 v[2:3], v[84:85], off offset:32
	v_mul_f32_e32 v112, v76, v6
	v_mul_f32_e32 v113, v77, v6
	v_mul_f32_e32 v114, v78, v6
	v_mul_f32_e32 v115, v79, v6
	s_waitcnt vmcnt(15)
	v_lshlrev_b32_e32 v116, 16, v86
	v_and_b32_e32 v117, 0xffff0000, v86
	v_lshlrev_b32_e32 v118, 16, v87
	v_and_b32_e32 v119, 0xffff0000, v87
	v_mul_f32_e32 v112, v112, v116
	v_mul_f32_e32 v113, v113, v117
	v_mul_f32_e32 v114, v114, v118
	v_mul_f32_e32 v115, v115, v119
	v_cvt_pk_bf16_f32 v86, v112, v113
	v_cvt_pk_bf16_f32 v87, v114, v115
	global_store_dwordx2 v[2:3], v[86:87], off offset:48
	v_mul_f32_e32 v112, v48, v6
	v_mul_f32_e32 v113, v49, v6
	v_mul_f32_e32 v114, v50, v6
	v_mul_f32_e32 v115, v51, v6
	s_waitcnt vmcnt(15)
	v_lshlrev_b32_e32 v116, 16, v88
	v_and_b32_e32 v117, 0xffff0000, v88
	v_lshlrev_b32_e32 v118, 16, v89
	v_and_b32_e32 v119, 0xffff0000, v89
	v_mul_f32_e32 v112, v112, v116
	v_mul_f32_e32 v113, v113, v117
	v_mul_f32_e32 v114, v114, v118
	v_mul_f32_e32 v115, v115, v119
	v_cvt_pk_bf16_f32 v88, v112, v113
	v_cvt_pk_bf16_f32 v89, v114, v115
	global_store_dwordx2 v[2:3], v[88:89], off offset:64
	v_mul_f32_e32 v112, v52, v6
	v_mul_f32_e32 v113, v53, v6
	v_mul_f32_e32 v114, v54, v6
	v_mul_f32_e32 v115, v55, v6
	s_waitcnt vmcnt(15)
	v_lshlrev_b32_e32 v116, 16, v90
	v_and_b32_e32 v117, 0xffff0000, v90
	v_lshlrev_b32_e32 v118, 16, v91
	v_and_b32_e32 v119, 0xffff0000, v91
	v_mul_f32_e32 v112, v112, v116
	v_mul_f32_e32 v113, v113, v117
	v_mul_f32_e32 v114, v114, v118
	v_mul_f32_e32 v115, v115, v119
	v_cvt_pk_bf16_f32 v90, v112, v113
	v_cvt_pk_bf16_f32 v91, v114, v115
	global_store_dwordx2 v[2:3], v[90:91], off offset:80
	v_mul_f32_e32 v112, v56, v6
	v_mul_f32_e32 v113, v57, v6
	v_mul_f32_e32 v114, v58, v6
	v_mul_f32_e32 v115, v59, v6
	s_waitcnt vmcnt(15)
; __device__ __forceinline__ unsigned cvtpk(float lo, float hi) { unsigned r; asm("v_cvt_pk_bf16_f32 %0, %1, %2" : "=v"(r) : "v"(lo), "v"(hi)); return r; }
; __device__ __forceinline__ float bf_lo(unsigned w) { return __uint_as_float(w << 16); }
; __device__ __forceinline__ float bf_hi(unsigned w) { return __uint_as_float(w & 0xffff0000u); }
; template <int MODE>
; __device__ __forceinline__ void attn_unit(LAS char* lds, const AttnPtrs& A, int b, int qb) {
;     ...
;     const bf16_t* grow = A.G + qrow * 2048; bf16_t* orow = A.Go + qrow * 2048;
; #pragma unroll
;     for (int c = 0; c < 4; ++c)
; #pragma unroll
;         for (int rr = 0; rr < 4; ++rr) {
;             const int dv = 32 * c + 8 * rr + 4 * hi;
;             const u32x2 g = *(const u32x2*)(grow + dv);
;             float v[4];
; #pragma unroll
;             for (int e = 0; e < 4; ++e) v[e] = o1[c][4 * rr + e];
;             if (MODE == 2) { const f32x4 sg = *(const f32x4*)(A.subg + dv);
; #pragma unroll
;                 for (int e = 0; e < 4; ++e) v[e] *= rstd * sg[e]; }
;             else {
; #pragma unroll
;                 for (int e = 0; e < 4; ++e) v[e] *= i1; }
;             u32x2 w; w.x = cvtpk(v[0] * bf_lo(g.x), v[1] * bf_hi(g.x)); w.y = cvtpk(v[2] * bf_lo(g.y), v[3] * bf_hi(g.y));
;             *(u32x2*)(orow + dv) = w;
	v_lshlrev_b32_e32 v116, 16, v92
	v_and_b32_e32 v117, 0xffff0000, v92
	v_lshlrev_b32_e32 v118, 16, v93
	v_and_b32_e32 v119, 0xffff0000, v93
	v_mul_f32_e32 v112, v112, v116
	v_mul_f32_e32 v113, v113, v117
	v_mul_f32_e32 v114, v114, v118
	v_mul_f32_e32 v115, v115, v119
	v_cvt_pk_bf16_f32 v92, v112, v113
	v_cvt_pk_bf16_f32 v93, v114, v115
	global_store_dwordx2 v[2:3], v[92:93], off offset:96
	v_mul_f32_e32 v112, v60, v6
	v_mul_f32_e32 v113, v61, v6
	v_mul_f32_e32 v114, v62, v6
	v_mul_f32_e32 v115, v63, v6
	s_waitcnt vmcnt(15)
	v_lshlrev_b32_e32 v116, 16, v94
	v_and_b32_e32 v117, 0xffff0000, v94
	v_lshlrev_b32_e32 v118, 16, v95
	v_and_b32_e32 v119, 0xffff0000, v95
	v_mul_f32_e32 v112, v112, v116
	v_mul_f32_e32 v113, v113, v117
	v_mul_f32_e32 v114, v114, v118
	v_mul_f32_e32 v115, v115, v119
	v_cvt_pk_bf16_f32 v94, v112, v113
	v_cvt_pk_bf16_f32 v95, v114, v115
	global_store_dwordx2 v[2:3], v[94:95], off offset:112
	v_mul_f32_e32 v112, v32, v6
	v_mul_f32_e32 v113, v33, v6
	v_mul_f32_e32 v114, v34, v6
	v_mul_f32_e32 v115, v35, v6
	s_waitcnt vmcnt(15)
	v_lshlrev_b32_e32 v116, 16, v96
	v_and_b32_e32 v117, 0xffff0000, v96
	v_lshlrev_b32_e32 v118, 16, v97
	v_and_b32_e32 v119, 0xffff0000, v97
	v_mul_f32_e32 v112, v112, v116
	v_mul_f32_e32 v113, v113, v117
	v_mul_f32_e32 v114, v114, v118
	v_mul_f32_e32 v115, v115, v119
	v_cvt_pk_bf16_f32 v96, v112, v113
	v_cvt_pk_bf16_f32 v97, v114, v115
	global_store_dwordx2 v[2:3], v[96:97], off offset:128
	v_mul_f32_e32 v112, v36, v6
	v_mul_f32_e32 v113, v37, v6
	v_mul_f32_e32 v114, v38, v6
	v_mul_f32_e32 v115, v39, v6
	s_waitcnt vmcnt(15)
	v_lshlrev_b32_e32 v116, 16, v98
	v_and_b32_e32 v117, 0xffff0000, v98
	v_lshlrev_b32_e32 v118, 16, v99
	v_and_b32_e32 v119, 0xffff0000, v99
	v_mul_f32_e32 v112, v112, v116
	v_mul_f32_e32 v113, v113, v117
	v_mul_f32_e32 v114, v114, v118
	v_mul_f32_e32 v115, v115, v119
	v_cvt_pk_bf16_f32 v98, v112, v113
	v_cvt_pk_bf16_f32 v99, v114, v115
	global_store_dwordx2 v[2:3], v[98:99], off offset:144
	v_mul_f32_e32 v112, v40, v6
	v_mul_f32_e32 v113, v41, v6
	v_mul_f32_e32 v114, v42, v6
	v_mul_f32_e32 v115, v43, v6
	s_waitcnt vmcnt(15)
	v_lshlrev_b32_e32 v116, 16, v100
	v_and_b32_e32 v117, 0xffff0000, v100
	v_lshlrev_b32_e32 v118, 16, v101
	v_and_b32_e32 v119, 0xffff0000, v101
	v_mul_f32_e32 v112, v112, v116
	v_mul_f32_e32 v113, v113, v117
	v_mul_f32_e32 v114, v114, v118
	v_mul_f32_e32 v115, v115, v119
	v_cvt_pk_bf16_f32 v100, v112, v113
	v_cvt_pk_bf16_f32 v101, v114, v115
	global_store_dwordx2 v[2:3], v[100:101], off offset:160
	v_mul_f32_e32 v112, v44, v6
	v_mul_f32_e32 v113, v45, v6
	v_mul_f32_e32 v114, v46, v6
	v_mul_f32_e32 v115, v47, v6
	s_waitcnt vmcnt(15)
	v_lshlrev_b32_e32 v116, 16, v102
	v_and_b32_e32 v117, 0xffff0000, v102
	v_lshlrev_b32_e32 v118, 16, v103
	v_and_b32_e32 v119, 0xffff0000, v103
	v_mul_f32_e32 v112, v112, v116
	v_mul_f32_e32 v113, v113, v117
	v_mul_f32_e32 v114, v114, v118
	v_mul_f32_e32 v115, v115, v119
	v_cvt_pk_bf16_f32 v102, v112, v113
	v_cvt_pk_bf16_f32 v103, v114, v115
	global_store_dwordx2 v[2:3], v[102:103], off offset:176
	v_mul_f32_e32 v112, v16, v6
	v_mul_f32_e32 v113, v17, v6
	v_mul_f32_e32 v114, v18, v6
	v_mul_f32_e32 v115, v19, v6
	s_waitcnt vmcnt(15)
	v_lshlrev_b32_e32 v116, 16, v104
	v_and_b32_e32 v117, 0xffff0000, v104
	v_lshlrev_b32_e32 v118, 16, v105
	v_and_b32_e32 v119, 0xffff0000, v105
	v_mul_f32_e32 v112, v112, v116
	v_mul_f32_e32 v113, v113, v117
	v_mul_f32_e32 v114, v114, v118
	v_mul_f32_e32 v115, v115, v119
	v_cvt_pk_bf16_f32 v104, v112, v113
	v_cvt_pk_bf16_f32 v105, v114, v115
	global_store_dwordx2 v[2:3], v[104:105], off offset:192
	v_mul_f32_e32 v112, v20, v6
	v_mul_f32_e32 v113, v21, v6
	v_mul_f32_e32 v114, v22, v6
	v_mul_f32_e32 v115, v23, v6
	s_waitcnt vmcnt(15)
	v_lshlrev_b32_e32 v116, 16, v106
	v_and_b32_e32 v117, 0xffff0000, v106
	v_lshlrev_b32_e32 v118, 16, v107
	v_and_b32_e32 v119, 0xffff0000, v107
	v_mul_f32_e32 v112, v112, v116
	v_mul_f32_e32 v113, v113, v117
	v_mul_f32_e32 v114, v114, v118
	v_mul_f32_e32 v115, v115, v119
	v_cvt_pk_bf16_f32 v106, v112, v113
	v_cvt_pk_bf16_f32 v107, v114, v115
	global_store_dwordx2 v[2:3], v[106:107], off offset:208
	v_mul_f32_e32 v112, v24, v6
	v_mul_f32_e32 v113, v25, v6
	v_mul_f32_e32 v114, v26, v6
	v_mul_f32_e32 v115, v27, v6
	s_waitcnt vmcnt(15)
	v_lshlrev_b32_e32 v116, 16, v108
	v_and_b32_e32 v117, 0xffff0000, v108
	v_lshlrev_b32_e32 v118, 16, v109
	v_and_b32_e32 v119, 0xffff0000, v109
	v_mul_f32_e32 v112, v112, v116
	v_mul_f32_e32 v113, v113, v117
	v_mul_f32_e32 v114, v114, v118
	v_mul_f32_e32 v115, v115, v119
	v_cvt_pk_bf16_f32 v108, v112, v113
	v_cvt_pk_bf16_f32 v109, v114, v115
	global_store_dwordx2 v[2:3], v[108:109], off offset:224
	v_mul_f32_e32 v112, v28, v6
	v_mul_f32_e32 v113, v29, v6
	v_mul_f32_e32 v114, v30, v6
	v_mul_f32_e32 v115, v31, v6
	s_waitcnt vmcnt(15)
	v_lshlrev_b32_e32 v116, 16, v110
	v_and_b32_e32 v117, 0xffff0000, v110
	v_lshlrev_b32_e32 v118, 16, v111
	v_and_b32_e32 v119, 0xffff0000, v111
	v_mul_f32_e32 v112, v112, v116
	v_mul_f32_e32 v113, v113, v117
	v_mul_f32_e32 v114, v114, v118
	v_mul_f32_e32 v115, v115, v119
	v_cvt_pk_bf16_f32 v110, v112, v113
	v_cvt_pk_bf16_f32 v111, v114, v115
	global_store_dwordx2 v[2:3], v[110:111], off offset:240
